# prep gating loop: v_readlane broadcasts issued eight ahead into eight SGPRs (decouples the SGPR write from the dependent fma chain); otherwise the v22 kernel
# speedup vs baseline: 1.0067x; 1.0026x over previous
; __device__ __forceinline__ void prep_phase(const Args& a, LAS unsigned char* lds, int tid, int lane, int wave) {
;     ...
;             for (int n = 0; n < blk; ++n) {
;                 const float* kb = KBAR + ((size_t)(bh * 32 + n)) * 64; float gsum = 0.f;
; #pragma unroll
;                 for (int d = 0; d < 64; ++d) gsum += q[d] * kb[d];
;                 if (gsum > g0) { g2 = g1; i2 = i1; g1 = g0; i1 = i0; g0 = gsum; i0 = n; }
;                 else if (gsum > g1) { g2 = g1; i2 = i1; g1 = gsum; i1 = n; }
;                 else if (gsum > g2) { g2 = gsum; i2 = n; }
;             }
.LBB0_561:
	s_waitcnt lgkmcnt(0)
	v_mov_b32_e32 v138, v139
	v_add_u32_e32 v143, 0x100, v143
	ds_read_b32 v139, v143
	v_readlane_b32 s44, v138, 0
	v_readlane_b32 s45, v138, 1
	v_readlane_b32 s46, v138, 2
	v_readlane_b32 s47, v138, 3
	v_readlane_b32 s48, v138, 4
	v_readlane_b32 s49, v138, 5
	v_readlane_b32 s50, v138, 6
	v_readlane_b32 s51, v138, 7
	v_fma_f32 v74, s44, v1, 0
	v_fmac_f32_e32 v74, s45, v17
	v_fmac_f32_e32 v74, s46, v18
	v_fmac_f32_e32 v74, s47, v19
	v_fmac_f32_e32 v74, s48, v20
	v_fmac_f32_e32 v74, s49, v21
	v_fmac_f32_e32 v74, s50, v22
	v_fmac_f32_e32 v74, s51, v23
	v_readlane_b32 s44, v138, 8
	v_readlane_b32 s45, v138, 9
	v_readlane_b32 s46, v138, 10
	v_readlane_b32 s47, v138, 11
	v_readlane_b32 s48, v138, 12
	v_readlane_b32 s49, v138, 13
	v_readlane_b32 s50, v138, 14
	v_readlane_b32 s51, v138, 15
	v_fmac_f32_e32 v74, s44, v24
	v_fmac_f32_e32 v74, s45, v25
	v_fmac_f32_e32 v74, s46, v26
	v_fmac_f32_e32 v74, s47, v27
	v_fmac_f32_e32 v74, s48, v28
	v_fmac_f32_e32 v74, s49, v29
	v_fmac_f32_e32 v74, s50, v30
	v_fmac_f32_e32 v74, s51, v31
	v_readlane_b32 s44, v138, 16
	v_readlane_b32 s45, v138, 17
	v_readlane_b32 s46, v138, 18
	v_readlane_b32 s47, v138, 19
	v_readlane_b32 s48, v138, 20
	v_readlane_b32 s49, v138, 21
	v_readlane_b32 s50, v138, 22
	v_readlane_b32 s51, v138, 23
	v_fmac_f32_e32 v74, s44, v32
	v_fmac_f32_e32 v74, s45, v33
	v_fmac_f32_e32 v74, s46, v34
	v_fmac_f32_e32 v74, s47, v35
	v_fmac_f32_e32 v74, s48, v36
	v_fmac_f32_e32 v74, s49, v37
	v_fmac_f32_e32 v74, s50, v38
	v_fmac_f32_e32 v74, s51, v39
	v_readlane_b32 s44, v138, 24
	v_readlane_b32 s45, v138, 25
	v_readlane_b32 s46, v138, 26
	v_readlane_b32 s47, v138, 27
	v_readlane_b32 s48, v138, 28
	v_readlane_b32 s49, v138, 29
	v_readlane_b32 s50, v138, 30
	v_readlane_b32 s51, v138, 31
	v_fmac_f32_e32 v74, s44, v40
	v_fmac_f32_e32 v74, s45, v41
	v_fmac_f32_e32 v74, s46, v42
	v_fmac_f32_e32 v74, s47, v43
	v_fmac_f32_e32 v74, s48, v45
	v_fmac_f32_e32 v74, s49, v46
	v_fmac_f32_e32 v74, s50, v47
	v_fmac_f32_e32 v74, s51, v48
	v_readlane_b32 s44, v138, 32
	v_readlane_b32 s45, v138, 33
	v_readlane_b32 s46, v138, 34
	v_readlane_b32 s47, v138, 35
	v_readlane_b32 s48, v138, 36
	v_readlane_b32 s49, v138, 37
	v_readlane_b32 s50, v138, 38
	v_readlane_b32 s51, v138, 39
	v_fmac_f32_e32 v74, s44, v49
	v_fmac_f32_e32 v74, s45, v51
	v_fmac_f32_e32 v74, s46, v52
	v_fmac_f32_e32 v74, s47, v53
	v_fmac_f32_e32 v74, s48, v54
	v_fmac_f32_e32 v74, s49, v55
	v_fmac_f32_e32 v74, s50, v56
	v_fmac_f32_e32 v74, s51, v57
	v_readlane_b32 s44, v138, 40
	v_readlane_b32 s45, v138, 41
	v_readlane_b32 s46, v138, 42
	v_readlane_b32 s47, v138, 43
	v_readlane_b32 s48, v138, 44
	v_readlane_b32 s49, v138, 45
	v_readlane_b32 s50, v138, 46
	v_readlane_b32 s51, v138, 47
	v_fmac_f32_e32 v74, s44, v58
	v_fmac_f32_e32 v74, s45, v59
	v_fmac_f32_e32 v74, s46, v60
	v_fmac_f32_e32 v74, s47, v61
	v_fmac_f32_e32 v74, s48, v62
	v_fmac_f32_e32 v74, s49, v63
	v_fmac_f32_e32 v74, s50, v64
	v_fmac_f32_e32 v74, s51, v65
	v_readlane_b32 s44, v138, 48
	v_readlane_b32 s45, v138, 49
	v_readlane_b32 s46, v138, 50
	v_readlane_b32 s47, v138, 52
	v_readlane_b32 s48, v138, 53
	v_readlane_b32 s49, v138, 51
	v_fmac_f32_e32 v74, s44, v66
	v_fmac_f32_e32 v74, s45, v67
	v_fmac_f32_e32 v74, s46, v68
	v_mul_f32_e32 v78, s47, v2
	v_mul_f32_e32 v79, s48, v3
	v_fmac_f32_e32 v74, s49, v69
	v_add_f32_e32 v74, v74, v78
	v_readlane_b32 s44, v138, 54
	v_readlane_b32 s45, v138, 55
	v_mul_f32_e32 v80, s44, v4
	v_mul_f32_e32 v81, s45, v5
	v_add_f32_e32 v74, v74, v79
	v_add_f32_e32 v74, v74, v80
	v_readlane_b32 s44, v138, 56
	v_readlane_b32 s45, v138, 57
	v_mul_f32_e32 v82, s44, v6
	v_mul_f32_e32 v83, s45, v7
	v_add_f32_e32 v74, v74, v81
	v_add_f32_e32 v74, v74, v82
	v_readlane_b32 s44, v138, 58
	v_readlane_b32 s45, v138, 59
	v_mul_f32_e32 v84, s44, v8
	v_mul_f32_e32 v85, s45, v9
	v_add_f32_e32 v74, v74, v83
	v_add_f32_e32 v74, v74, v84
	v_readlane_b32 s44, v138, 60
	v_readlane_b32 s45, v138, 61
	v_mul_f32_e32 v86, s44, v10
	v_mul_f32_e32 v87, s45, v11
	v_add_f32_e32 v74, v74, v85
	v_add_f32_e32 v74, v74, v86
	v_readlane_b32 s44, v138, 62
	v_readlane_b32 s45, v138, 63
	v_mul_f32_e32 v88, s44, v14
	v_mul_f32_e32 v89, s45, v15
	v_add_f32_e32 v74, v74, v87
	v_add_f32_e32 v74, v74, v88
	v_add_f32_e32 v74, v74, v89
	v_cmp_ngt_f32_e32 vcc, v74, v73
	v_mov_b32_e32 v75, s6
	s_and_saveexec_b64 s[26:27], vcc
	s_cbranch_execz .LBB0_567
	v_cmp_ngt_f32_e32 vcc, v74, v72
	v_mov_b32_e32 v76, s6
	s_and_saveexec_b64 s[28:29], vcc
	s_cbranch_execz .LBB0_566
	v_cmp_gt_f32_e32 vcc, v74, v50
	s_and_saveexec_b64 s[8:9], vcc
	v_mov_b32_e32 v44, s6
	v_mov_b32_e32 v50, v74
	s_or_b64 exec, exec, s[8:9]
	v_mov_b32_e32 v76, v70
	v_mov_b32_e32 v74, v72
	v_mov_b32_e32 v72, v50
	v_mov_b32_e32 v70, v44
